# DN epilogue head: next-norm modulation vector loads batched into one round trip
# speedup vs baseline: 1.0036x; 1.0006x over previous
.LBB0_846:
	s_ashr_i32 s6, s30, 4
	v_lshl_or_b32 v198, s31, 8, v217
	s_mul_i32 s50, s6, 0x6000
	s_mul_hi_i32 s31, s6, 0x6000
	s_add_u32 s6, s60, s50
	v_ashrrev_i32_e32 v199, 31, v198
	s_addc_u32 s7, s61, s31
	v_lshlrev_b64 v[68:69], 2, v[198:199]
	v_lshl_add_u64 v[80:81], s[6:7], 0, v[68:69]
	global_load_dwordx4 v[76:79], v[80:81], off
	s_add_u32 s6, s26, s50
	s_addc_u32 s7, s62, s31
	v_lshl_add_u64 v[144:145], s[20:21], 0, v[68:69]
	v_lshl_add_u64 v[146:147], s[6:7], 0, v[68:69]
	global_load_dwordx4 v[84:87], v[80:81], off offset:16
	global_load_dwordx4 v[68:71], v[80:81], off offset:512
	v_cmp_ne_u32_e64 s[6:7], 1, v214
	v_mov_b32_e32 v190, 0
	v_mov_b32_e32 v192, 0
	v_mov_b32_e32 v193, 0
	v_mov_b32_e32 v194, 0
	v_mov_b32_e32 v195, 0
	v_mov_b32_e32 v191, 0
	v_mov_b32_e32 v200, 0
	v_mov_b32_e32 v201, 0
	v_mov_b32_e32 v184, 0
	v_mov_b32_e32 v186, 0
	v_mov_b32_e32 v187, 0
	v_mov_b32_e32 v188, 0
	v_mov_b32_e32 v189, 0
	v_mov_b32_e32 v185, 0
	v_mov_b32_e32 v196, 0
	v_mov_b32_e32 v197, 0
	s_andn2_b64 vcc, exec, s[10:11]
	s_cbranch_vccnz .Ldn_h1
	global_load_dwordx4 v[174:177], v[146:147], off
	global_load_dwordx4 v[178:181], v[144:145], off
.Ldn_h1:
	s_and_b64 vcc, exec, s[6:7]
	s_cbranch_vccnz .Ldn_h2
	global_load_dwordx4 v[228:231], v[146:147], off offset:16
	global_load_dwordx4 v[238:241], v[144:145], off offset:16
	global_load_dwordx4 v[242:245], v[146:147], off offset:512
	global_load_dwordx4 v[246:249], v[144:145], off offset:512
	global_load_dwordx4 v[160:163], v[146:147], off offset:528
	global_load_dwordx4 v[164:167], v[144:145], off offset:528
.Ldn_h2:
	global_load_dwordx4 v[80:83], v[80:81], off offset:528
	s_waitcnt vmcnt(0)
	s_andn2_b64 vcc, exec, s[10:11]
	s_cbranch_vccnz .Ldn_h3
	v_pk_add_f32 v[176:177], v[176:177], 1.0 op_sel_hi:[1,0]
	v_pk_add_f32 v[174:175], v[174:175], 1.0 op_sel_hi:[1,0]
	v_pk_mul_f32 v[194:195], v[180:181], v[176:177]
	v_pk_mul_f32 v[192:193], v[178:179], v[174:175]
.Ldn_h3:
	s_and_b64 vcc, exec, s[6:7]
	s_cbranch_vccnz .LBB0_854
	v_pk_add_f32 v[230:231], v[230:231], 1.0 op_sel_hi:[1,0]
	v_pk_add_f32 v[228:229], v[228:229], 1.0 op_sel_hi:[1,0]
	v_pk_mul_f32 v[200:201], v[240:241], v[230:231]
	v_pk_mul_f32 v[190:191], v[238:239], v[228:229]
	v_pk_add_f32 v[244:245], v[244:245], 1.0 op_sel_hi:[1,0]
	v_pk_add_f32 v[242:243], v[242:243], 1.0 op_sel_hi:[1,0]
	v_pk_mul_f32 v[188:189], v[248:249], v[244:245]
	v_pk_mul_f32 v[186:187], v[246:247], v[242:243]
	v_pk_add_f32 v[162:163], v[162:163], 1.0 op_sel_hi:[1,0]
	v_pk_add_f32 v[160:161], v[160:161], 1.0 op_sel_hi:[1,0]
	v_pk_mul_f32 v[196:197], v[166:167], v[162:163]
	v_pk_mul_f32 v[184:185], v[164:165], v[160:161]
